# tile-major SwiGLU output only (write-through stores kept)
# baseline (speedup 1.0000x reference)
.LBB0_149:
	v_readlane_b32 s54, v243, 5
	s_mov_b32 s0, 0
	s_mov_b64 s[22:23], -1
	s_mov_b32 s70, 1
	s_movk_i32 s29, 0x400
	s_mov_b32 s58, 0.5
	s_mov_b32 s47, 0
	s_mov_b32 s74, 4
	s_movk_i32 s39, 0x40
	s_movk_i32 s38, 0xb00
	v_readlane_b32 s55, v243, 6
	s_mov_b64 s[56:57], 0
	s_mov_b32 s59, 0
	v_writelane_b32 v243, s0, 26
	s_mov_b64 s[50:51], 0
	s_mov_b64 s[62:63], 0
	s_branch .LBB0_151

.LBB0_156:
	s_andn2_b64 vcc, exec, s[22:23]
	s_cbranch_vccnz .LBB0_228
	s_movk_i32 s100, 0x80
	s_mov_b32 s101, 0
	s_cmpk_eq_u32 s38, 0xb00
	s_cselect_b32 s100, 0x8000, s100
	s_waitcnt lgkmcnt(0)
	v_bfe_i32 v3, v14, 27, 1
	v_lshlrev_b32_e32 v1, 4, v14
	v_lshrrev_b32_e32 v3, 22, v3
	v_add_u32_e32 v3, v1, v3
	v_and_b32_e32 v3, 0xfffffc00, v3
	v_ashrrev_i32_e32 v2, 31, v14
	v_sub_u32_e32 v3, v1, v3
	v_lshrrev_b32_e32 v2, 26, v2
	v_lshrrev_b32_e32 v4, 4, v3
	v_add_u32_e32 v2, v14, v2
	v_bitop3_b32 v4, v4, v3, 32 bitop3:0x6c
	v_ashrrev_i32_e32 v3, 31, v3
	v_ashrrev_i32_e32 v2, 6, v2
	v_lshrrev_b32_e32 v3, 26, v3
	v_lshlrev_b32_e32 v5, 3, v2
	v_add_u32_e32 v3, v4, v3
	v_and_b32_e32 v5, -16, v5
	v_ashrrev_i32_e32 v3, 6, v3
	v_lshlrev_b32_e32 v2, 5, v2
	v_add_u32_e32 v5, v3, v5
	v_and_b32_e32 v15, 32, v2
	v_mul_i32_i24_e32 v2, 64, v3
	v_sub_u32_e32 v2, v4, v2
	v_lshlrev_b32_e32 v4, 1, v5
	v_lshrrev_b32_e32 v6, 2, v5
	v_and_b32_e32 v3, 3, v3
	s_mov_b32 s2, 0x7fffffe0
	v_ashrrev_i16_sdwa v2, v222, sext(v2) dst_sel:DWORD dst_unused:UNUSED_PAD src0_sel:DWORD src1_sel:BYTE_0
	v_and_b32_e32 v4, 24, v4
	v_and_b32_e32 v6, 4, v6
	v_and_or_b32 v3, v5, s2, v3
	v_bfe_i32 v16, v2, 0, 16
	v_or3_b32 v3, v3, v6, v4
	v_add_u32_e32 v2, v15, v16
	v_mul_lo_u32 v17, v5, s39
	v_mul_lo_u32 v3, v3, s38
	v_add_u32_e32 v1, 0x2000, v1
	v_add_lshl_u32 v186, v2, v17, 1
	v_add_lshl_u32 v188, v3, v2, 1
	v_ashrrev_i32_e32 v2, 31, v1
	v_lshrrev_b32_e32 v2, 22, v2
	v_add_u32_e32 v2, v1, v2
	v_ashrrev_i32_e32 v2, 10, v2
	v_mul_i32_i24_e32 v3, 0x400, v2
	v_sub_u32_e32 v1, v1, v3
	v_lshrrev_b32_e32 v3, 4, v1
	v_bitop3_b32 v1, v3, v1, 32 bitop3:0x6c
	v_ashrrev_i32_e32 v4, 31, v1
	s_lshl_b32 s16, s39, 8
	v_lshrrev_b32_e32 v4, 26, v4
	s_lshl_b64 s[62:63], s[16:17], 1
	s_cmpk_eq_u32 s38, 0xb00
	s_cselect_b32 s62, 0x160000, s62
	s_ashr_i32 s21, s99, 31
	v_writelane_b32 v243, s59, 32
	v_lshlrev_b32_e32 v3, 3, v2
	v_add_u32_e32 v4, v1, v4
	s_mul_i32 s21, s62, s21
	s_mul_hi_u32 s22, s62, s99
	v_writelane_b32 v243, s56, 42
	v_and_b32_e32 v3, -16, v3
	v_ashrrev_i32_e32 v5, 6, v4
	s_add_i32 s21, s22, s21
	s_bfe_u32 s22, s39, 0x10017
	v_writelane_b32 v243, s57, 43
	s_ashr_i32 s1, s0, 6
	v_add_u32_e32 v3, v5, v3
	v_lshlrev_b32_e32 v2, 5, v2
	v_and_b32_e32 v5, 3, v5
	s_lshl_b32 s56, s38, 9
	s_mul_i32 s22, s22, s99
	v_and_b32_e32 v18, 32, v2
	v_and_b32_e32 v2, 0xc0, v4
	v_and_or_b32 v5, v3, s2, v5
	s_ashr_i32 s2, s0, 8
	s_lshl_b32 s69, s38, 8
	s_lshl_b32 s57, s1, 10
	s_add_i32 s21, s21, s22
	s_mul_i32 s23, s56, s88
	v_sub_u32_e32 v1, v1, v2
	v_lshlrev_b32_e32 v2, 1, v3
	v_lshrrev_b32_e32 v4, 2, v3
	s_mul_hi_i32 s22, s56, s88
	s_add_u32 s34, s48, s23
	v_ashrrev_i16_sdwa v1, v222, sext(v1) dst_sel:DWORD dst_unused:UNUSED_PAD src0_sel:DWORD src1_sel:BYTE_0
	v_and_b32_e32 v2, 24, v2
	v_and_b32_e32 v4, 4, v4
	s_addc_u32 s35, s49, s22
	s_add_i32 s90, s57, 0
	v_bfe_i32 v19, v1, 0, 16
	v_or3_b32 v2, v5, v4, v2
	s_add_i32 m0, s90, 0x10000
	v_add_u32_e32 v1, v18, v19
	v_mul_lo_u32 v2, v2, s38
	global_load_lds_dwordx4 v188, s[34:35]
	s_add_i32 m0, s90, 0x12000
	v_add_lshl_u32 v192, v2, v1, 1
	s_add_u32 s22, s34, s69
	global_load_lds_dwordx4 v192, s[34:35]
	s_addc_u32 s23, s35, 0
	s_add_i32 m0, s90, 0x14000
	v_mul_lo_u32 v20, v3, s39
	s_mul_i32 s39, s62, s99
	global_load_lds_dwordx4 v188, s[22:23]
	s_add_i32 m0, s90, 0x16000
	s_add_u32 s80, s54, s39
	v_mov_b32_e32 v189, v0
	v_mov_b32_e32 v193, v0
	s_addc_u32 s81, s55, s21
	s_add_i32 s60, s90, 0x2000
	v_lshl_add_u64 v[6:7], s[22:23], 0, v[188:189]
	v_lshl_add_u64 v[8:9], s[22:23], 0, v[192:193]
	global_load_lds_dwordx4 v192, s[22:23]
	s_mov_b32 m0, s90
	s_add_u32 s22, s80, s16
	v_add_lshl_u32 v190, v1, v20, 1
	global_load_lds_dwordx4 v186, s[80:81]
	s_mov_b32 m0, s60
	s_addc_u32 s23, s81, 0
	s_add_i32 s61, s90, 0x4000
	global_load_lds_dwordx4 v190, s[80:81]
	s_mov_b32 m0, s61
	s_add_i32 s71, s90, 0x6000
	global_load_lds_dwordx4 v186, s[22:23]
	s_mov_b32 m0, s71
	v_writelane_b32 v243, s47, 40
	global_load_lds_dwordx4 v190, s[22:23]
	v_writelane_b32 v243, s52, 44
	s_cmp_eq_u32 s2, 1
	v_mov_b32_e32 v187, v0
	v_writelane_b32 v243, s53, 45
	v_mov_b32_e32 v191, v0
	s_cselect_b64 s[22:23], -1, 0
	v_lshl_add_u64 v[2:3], s[34:35], 0, v[188:189]
	v_lshl_add_u64 v[4:5], s[34:35], 0, v[192:193]
	v_lshl_add_u64 v[10:11], s[80:81], 0, v[186:187]
	v_lshl_add_u64 v[12:13], s[80:81], 0, v[190:191]
	v_writelane_b32 v243, s22, 30
	s_cmp_lg_u32 s2, 1
	s_nop 0
	v_writelane_b32 v243, s23, 31
	s_cbranch_scc1 .LBB0_159
	s_barrier
.LBB0_159:
	s_add_i32 m0, s90, 0x18000
	v_lshl_add_u64 v[2:3], v[2:3], 0, s[36:37]
	s_waitcnt vmcnt(2)
	s_barrier
	global_load_lds_dwordx4 v[2:3], off
	v_lshl_add_u64 v[2:3], v[4:5], 0, s[36:37]
	s_add_i32 m0, s90, 0x1a000
	s_add_i32 s64, s90, 0x8000
	global_load_lds_dwordx4 v[2:3], off
	v_lshl_add_u64 v[2:3], v[10:11], 0, s[100:101]
	s_mov_b32 m0, s64
	s_add_i32 s65, s90, 0xa000
	global_load_lds_dwordx4 v[2:3], off
	v_lshl_add_u64 v[2:3], v[12:13], 0, s[100:101]
	s_mov_b32 m0, s65
	v_and_b32_e32 v4, 15, v14
	global_load_lds_dwordx4 v[2:3], off
	s_add_i32 m0, s90, 0x1c000
	v_lshl_add_u64 v[2:3], v[6:7], 0, s[36:37]
	global_load_lds_dwordx4 v[2:3], off
	v_lshl_add_u64 v[2:3], v[8:9], 0, s[36:37]
	s_add_i32 m0, s90, 0x1e000
	v_lshlrev_b32_e32 v5, 2, v14
	global_load_lds_dwordx4 v[2:3], off
	v_bfe_u32 v3, v14, 4, 2
	v_lshlrev_b32_e32 v233, 4, v3
	s_and_b32 s1, s1, 3
	s_lshr_b32 s91, s38, 6
	v_lshl_or_b32 v1, s2, 6, v4
	v_lshl_or_b32 v4, v4, 6, v233
	s_lshl_b32 s2, s2, 13
	v_and_b32_e32 v5, 32, v5
	v_bitop3_b32 v6, v4, s2, v5 bitop3:0xde
	s_lshl_b32 s2, s1, 12
	s_add_i32 s68, s91, -2
	s_cmpk_lt_u32 s0, 0x100
	s_cselect_b64 s[22:23], -1, 0
	v_writelane_b32 v243, s22, 28
	v_bitop3_b32 v234, v4, s2, v5 bitop3:0xde
	s_lshl_b32 s0, s1, 6
	v_writelane_b32 v243, s23, 29
	s_lshl_b32 s2, s74, 3
	v_writelane_b32 v243, s42, 46
	s_cmp_lg_u64 s[42:43], 0
	s_cselect_b64 s[22:23], -1, 0
	v_writelane_b32 v243, s43, 47
	v_readlane_b32 s40, v248, 54
	v_readlane_b32 s41, v248, 55
	v_writelane_b32 v243, s22, 48
	s_cmp_lg_u64 s[40:41], 0
	v_lshlrev_b32_e32 v2, 3, v3
	v_writelane_b32 v243, s23, 49
	s_cselect_b64 s[22:23], -1, 0
	s_abs_i32 s52, s2
	v_cmp_eq_u32_e64 s[38:39], 0, v3
	v_cvt_f32_u32_e32 v3, s52
	v_readlane_b32 s42, v248, 56
	v_readlane_b32 s43, v248, 57
	s_and_b32 s41, s41, 0xffff
	v_rcp_iflag_f32_e32 v3, v3
	v_writelane_b32 v248, s40, 54
	v_writelane_b32 v243, s22, 50
	v_or_b32_e32 v236, s0, v2
	v_writelane_b32 v248, s41, 55
	v_mul_f32_e32 v3, 0x4f7ffffe, v3
	v_writelane_b32 v243, s23, 51
	v_writelane_b32 v248, s42, 56
	v_cvt_u32_f32_e32 v3, v3
	v_writelane_b32 v248, s43, 57
	v_readlane_b32 s40, v243, 5
	v_readlane_b32 s41, v243, 6
	v_writelane_b32 v243, s0, 52
	s_mov_b32 s0, s74
	v_writelane_b32 v243, s0, 53
	s_bfe_i32 s0, s0, 0x1001c
	v_lshl_or_b32 v237, s1, 5, v2
	v_writelane_b32 v243, s0, 38
	s_sub_i32 s0, 0, s52
	v_readfirstlane_b32 s1, v3
	v_add_u32_e32 v3, v17, v15
	s_waitcnt vmcnt(6)
	s_mul_i32 s0, s0, s1
	v_add_lshl_u32 v4, v3, v16, 1
	v_mov_b32_e32 v5, v0
	v_add_u32_e32 v3, v20, v18
	s_mul_hi_u32 s0, s1, s0
	v_lshl_add_u64 v[194:195], s[16:17], 0, v[4:5]
	v_add_lshl_u32 v4, v3, v19, 1
	s_mov_b32 s46, 0
	v_or_b32_e32 v235, 64, v233
	s_mov_b32 s45, s17
	s_lshl_b32 s22, s29, 15
	s_mov_b32 s23, s43
	s_and_b32 s21, s41, 0xffff
	s_mov_b32 s28, s2
	s_mov_b32 s59, s58
	s_mov_b32 s74, s58
	s_mov_b32 s75, s58
	s_mov_b32 s84, s58
	s_mov_b32 s85, s58
	s_add_i32 s0, s1, s0
	s_lshl_b32 s53, s29, 4
	v_lshl_add_u64 v[196:197], s[16:17], 0, v[4:5]
	v_add_u32_e32 v238, 0, v6
	v_lshlrev_b32_e32 v239, 2, v2
	s_barrier
	v_writelane_b32 v243, s0, 34
	s_branch .LBB0_162

.LBB0_168:
	s_add_u32 s80, s80, s100
	s_addc_u32 s81, s81, 0
	s_add_u32 vcc_lo, s34, 0x100
	v_mov_b32_e32 v2, 0
	s_addc_u32 vcc_hi, s35, 0
	s_mov_b32 s34, 0
	v_mov_b32_e32 v3, v2
	v_mov_b32_e32 v4, v2
	v_mov_b32_e32 v5, v2
	v_mov_b32_e32 v6, v2
	v_mov_b32_e32 v7, v2
	v_mov_b32_e32 v8, v2
	v_mov_b32_e32 v9, v2
	v_mov_b32_e32 v18, v2
	v_mov_b32_e32 v19, v2
	v_mov_b32_e32 v20, v2
	v_mov_b32_e32 v21, v2
	v_mov_b32_e32 v22, v2
	v_mov_b32_e32 v23, v2
	v_mov_b32_e32 v24, v2
	v_mov_b32_e32 v25, v2
	v_mov_b32_e32 v34, v2
	v_mov_b32_e32 v35, v2
	v_mov_b32_e32 v36, v2
	v_mov_b32_e32 v37, v2
	v_mov_b32_e32 v38, v2
	v_mov_b32_e32 v39, v2
	v_mov_b32_e32 v40, v2
	v_mov_b32_e32 v41, v2
	v_mov_b32_e32 v50, v2
	v_mov_b32_e32 v51, v2
	v_mov_b32_e32 v52, v2
	v_mov_b32_e32 v53, v2
	v_mov_b32_e32 v54, v2
	v_mov_b32_e32 v55, v2
	v_mov_b32_e32 v56, v2
	v_mov_b32_e32 v57, v2
	v_mov_b32_e32 v10, v2
	v_mov_b32_e32 v11, v2
	v_mov_b32_e32 v12, v2
	v_mov_b32_e32 v13, v2
	v_mov_b32_e32 v14, v2
	v_mov_b32_e32 v15, v2
	v_mov_b32_e32 v16, v2
	v_mov_b32_e32 v17, v2
	v_mov_b32_e32 v26, v2
	v_mov_b32_e32 v27, v2
	v_mov_b32_e32 v28, v2
	v_mov_b32_e32 v29, v2
	v_mov_b32_e32 v30, v2
	v_mov_b32_e32 v31, v2
	v_mov_b32_e32 v32, v2
	v_mov_b32_e32 v33, v2
	v_mov_b32_e32 v42, v2
	v_mov_b32_e32 v43, v2
	v_mov_b32_e32 v44, v2
	v_mov_b32_e32 v45, v2
	v_mov_b32_e32 v46, v2
	v_mov_b32_e32 v47, v2
	v_mov_b32_e32 v48, v2
	v_mov_b32_e32 v49, v2
	v_mov_b32_e32 v58, v2
	v_mov_b32_e32 v59, v2
	v_mov_b32_e32 v60, v2
	v_mov_b32_e32 v61, v2
	v_mov_b32_e32 v62, v2
	v_mov_b32_e32 v63, v2
	v_mov_b32_e32 v64, v2
	v_mov_b32_e32 v65, v2
	s_waitcnt vmcnt(0)
	v_mov_b32_e32 v66, v2
	v_mov_b32_e32 v67, v2
	v_mov_b32_e32 v68, v2
	v_mov_b32_e32 v69, v2
	v_mov_b32_e32 v70, v2
	v_mov_b32_e32 v71, v2
	v_mov_b32_e32 v72, v2
	v_mov_b32_e32 v73, v2
	v_mov_b32_e32 v82, v2
	v_mov_b32_e32 v83, v2
	v_mov_b32_e32 v84, v2
	v_mov_b32_e32 v85, v2
	v_mov_b32_e32 v86, v2
	v_mov_b32_e32 v87, v2
	v_mov_b32_e32 v88, v2
	v_mov_b32_e32 v89, v2
	v_mov_b32_e32 v98, v2
	v_mov_b32_e32 v99, v2
	v_mov_b32_e32 v100, v2
	v_mov_b32_e32 v101, v2
	v_mov_b32_e32 v106, v2
	v_mov_b32_e32 v107, v2
	v_mov_b32_e32 v108, v2
	v_mov_b32_e32 v109, v2
	v_mov_b32_e32 v110, v2
	v_mov_b32_e32 v111, v2
	v_mov_b32_e32 v112, v2
	v_mov_b32_e32 v113, v2
	v_mov_b32_e32 v114, v2
	v_mov_b32_e32 v115, v2
	v_mov_b32_e32 v116, v2
	v_mov_b32_e32 v117, v2
	v_mov_b32_e32 v74, v2
	v_mov_b32_e32 v75, v2
	v_mov_b32_e32 v76, v2
	v_mov_b32_e32 v77, v2
	v_mov_b32_e32 v78, v2
	v_mov_b32_e32 v79, v2
	v_mov_b32_e32 v80, v2
	v_mov_b32_e32 v81, v2
	v_mov_b32_e32 v90, v2
	v_mov_b32_e32 v91, v2
	v_mov_b32_e32 v92, v2
	v_mov_b32_e32 v93, v2
	v_mov_b32_e32 v94, v2
	v_mov_b32_e32 v95, v2
	v_mov_b32_e32 v96, v2
	v_mov_b32_e32 v97, v2
	v_mov_b32_e32 v102, v2
	v_mov_b32_e32 v103, v2
	v_mov_b32_e32 v104, v2
	v_mov_b32_e32 v105, v2
	v_mov_b32_e32 v118, v2
	v_mov_b32_e32 v119, v2
	v_mov_b32_e32 v120, v2
	v_mov_b32_e32 v121, v2
	v_mov_b32_e32 v122, v2
	v_mov_b32_e32 v123, v2
	v_mov_b32_e32 v124, v2
	v_mov_b32_e32 v125, v2
	v_mov_b32_e32 v126, v2
	v_mov_b32_e32 v127, v2
	v_mov_b32_e32 v128, v2
	v_mov_b32_e32 v129, v2
.LBB0_169:
	s_add_i32 s0, s34, 2
	s_add_u32 s1, s80, s100
	s_addc_u32 s35, s81, 0
	s_add_i32 s47, 0, 0x10000
	s_cmp_eq_u32 s68, s34
	s_cselect_b32 s35, s43, s35
	s_cselect_b32 s34, s42, s1
	s_cselect_b32 s67, s87, vcc_hi
	s_cselect_b32 s66, s86, vcc_lo
	s_add_i32 s1, 0, 0x14000
	v_add_u32_e32 v142, s47, v234
	v_add_u32_e32 v158, s1, v234
	s_waitcnt lgkmcnt(0)
	ds_read_b128 v[130:133], v142
	ds_read_b128 v[134:137], v142 offset:1024
	ds_read_b128 v[138:141], v142 offset:2048
	ds_read_b128 v[142:145], v142 offset:3072
	ds_read_b128 v[146:149], v158
	ds_read_b128 v[150:153], v158 offset:1024
	ds_read_b128 v[154:157], v158 offset:2048
	ds_read_b128 v[158:161], v158 offset:3072
	v_lshl_add_u64 v[206:207], s[80:81], 0, v[194:195]
	s_add_i32 m0, s90, 0xc000
	ds_read_b128 v[162:165], v238
	ds_read_b128 v[166:169], v238 offset:1024
	ds_read_b128 v[170:173], v238 offset:2048
	ds_read_b128 v[174:177], v238 offset:3072
	ds_read_b128 v[178:181], v238 offset:4096
	ds_read_b128 v[182:185], v238 offset:5120
	ds_read_b128 v[198:201], v238 offset:6144
	ds_read_b128 v[202:205], v238 offset:7168
	global_load_lds_dwordx4 v[206:207], off
	v_lshl_add_u64 v[206:207], s[80:81], 0, v[196:197]
	s_add_i32 m0, s90, 0xe000
	s_nop 0
	global_load_lds_dwordx4 v[206:207], off
	s_waitcnt vmcnt(8)
	s_waitcnt lgkmcnt(0)
	s_barrier
	s_setprio 1
	s_waitcnt lgkmcnt(0)
	v_mfma_f32_16x16x32_bf16 v[126:129], v[130:133], v[162:165], v[126:129]
	v_mfma_f32_16x16x32_bf16 v[122:125], v[138:141], v[162:165], v[122:125]
	v_mfma_f32_16x16x32_bf16 v[118:121], v[130:133], v[170:173], v[118:121]
	v_mfma_f32_16x16x32_bf16 v[102:105], v[138:141], v[170:173], v[102:105]
	v_mfma_f32_16x16x32_bf16 v[94:97], v[130:133], v[178:181], v[94:97]
	v_mfma_f32_16x16x32_bf16 v[90:93], v[138:141], v[178:181], v[90:93]
	v_mfma_f32_16x16x32_bf16 v[78:81], v[130:133], v[198:201], v[78:81]
	v_mfma_f32_16x16x32_bf16 v[74:77], v[138:141], v[198:201], v[74:77]
	v_mfma_f32_16x16x32_bf16 v[126:129], v[134:137], v[166:169], v[126:129]
	v_mfma_f32_16x16x32_bf16 v[122:125], v[142:145], v[166:169], v[122:125]
	v_mfma_f32_16x16x32_bf16 v[118:121], v[134:137], v[174:177], v[118:121]
	v_mfma_f32_16x16x32_bf16 v[102:105], v[142:145], v[174:177], v[102:105]
	v_mfma_f32_16x16x32_bf16 v[94:97], v[134:137], v[182:185], v[94:97]
	v_mfma_f32_16x16x32_bf16 v[90:93], v[142:145], v[182:185], v[90:93]
	v_mfma_f32_16x16x32_bf16 v[78:81], v[134:137], v[202:205], v[78:81]
	v_mfma_f32_16x16x32_bf16 v[74:77], v[142:145], v[202:205], v[74:77]
	s_setprio 0
	s_setprio 1
	v_mfma_f32_16x16x32_bf16 v[114:117], v[146:149], v[162:165], v[114:117]
	v_mfma_f32_16x16x32_bf16 v[110:113], v[154:157], v[162:165], v[110:113]
	v_mfma_f32_16x16x32_bf16 v[106:109], v[146:149], v[170:173], v[106:109]
	v_mfma_f32_16x16x32_bf16 v[98:101], v[154:157], v[170:173], v[98:101]
	v_mfma_f32_16x16x32_bf16 v[86:89], v[146:149], v[178:181], v[86:89]
	v_mfma_f32_16x16x32_bf16 v[82:85], v[154:157], v[178:181], v[82:85]
	v_mfma_f32_16x16x32_bf16 v[70:73], v[146:149], v[198:201], v[70:73]
	v_mfma_f32_16x16x32_bf16 v[66:69], v[154:157], v[198:201], v[66:69]
	v_mfma_f32_16x16x32_bf16 v[114:117], v[150:153], v[166:169], v[114:117]
	v_mfma_f32_16x16x32_bf16 v[110:113], v[158:161], v[166:169], v[110:113]
	v_mfma_f32_16x16x32_bf16 v[106:109], v[150:153], v[174:177], v[106:109]
	v_mfma_f32_16x16x32_bf16 v[98:101], v[158:161], v[174:177], v[98:101]
	v_mfma_f32_16x16x32_bf16 v[86:89], v[150:153], v[182:185], v[86:89]
	v_mfma_f32_16x16x32_bf16 v[82:85], v[158:161], v[182:185], v[82:85]
	v_mfma_f32_16x16x32_bf16 v[70:73], v[150:153], v[202:205], v[70:73]
	v_mfma_f32_16x16x32_bf16 v[66:69], v[158:161], v[202:205], v[66:69]
	s_setprio 0
	s_barrier
	s_add_i32 s47, s47, s57
	v_lshl_add_u64 v[206:207], s[66:67], 0, v[188:189]
	s_mov_b32 m0, s47
	ds_read_b128 v[162:165], v238 offset:16384
	ds_read_b128 v[166:169], v238 offset:17408
	ds_read_b128 v[170:173], v238 offset:18432
	ds_read_b128 v[174:177], v238 offset:19456
	ds_read_b128 v[178:181], v238 offset:20480
	ds_read_b128 v[182:185], v238 offset:21504
	ds_read_b128 v[198:201], v238 offset:22528
	ds_read_b128 v[202:205], v238 offset:23552
	global_load_lds_dwordx4 v[206:207], off
	s_add_i32 m0, s47, 0x2000
	v_lshl_add_u64 v[208:209], s[66:67], 0, v[192:193]
	s_add_u32 s66, s66, s69
	s_addc_u32 s67, s67, 0
	s_add_i32 s1, s1, s57
	global_load_lds_dwordx4 v[208:209], off
	v_lshl_add_u64 v[210:211], s[66:67], 0, v[188:189]
	s_mov_b32 m0, s1
	v_lshl_add_u64 v[212:213], s[66:67], 0, v[192:193]
	global_load_lds_dwordx4 v[210:211], off
	s_add_i32 m0, s1, 0x2000
	v_lshl_add_u64 v[214:215], s[34:35], 0, v[186:187]
	global_load_lds_dwordx4 v[212:213], off
	s_mov_b32 m0, s90
	v_lshl_add_u64 v[216:217], s[34:35], 0, v[190:191]
	global_load_lds_dwordx4 v[214:215], off
	s_mov_b32 m0, s60
	s_nop 0
	global_load_lds_dwordx4 v[216:217], off
	s_waitcnt vmcnt(8)
	s_waitcnt lgkmcnt(0)
	s_barrier
	s_setprio 1
	s_waitcnt lgkmcnt(0)
	v_mfma_f32_16x16x32_bf16 v[62:65], v[130:133], v[162:165], v[62:65]
	v_mfma_f32_16x16x32_bf16 v[58:61], v[138:141], v[162:165], v[58:61]
	v_mfma_f32_16x16x32_bf16 v[46:49], v[130:133], v[170:173], v[46:49]
	v_mfma_f32_16x16x32_bf16 v[42:45], v[138:141], v[170:173], v[42:45]
	v_mfma_f32_16x16x32_bf16 v[30:33], v[130:133], v[178:181], v[30:33]
	v_mfma_f32_16x16x32_bf16 v[26:29], v[138:141], v[178:181], v[26:29]
	v_mfma_f32_16x16x32_bf16 v[14:17], v[130:133], v[198:201], v[14:17]
	v_mfma_f32_16x16x32_bf16 v[10:13], v[138:141], v[198:201], v[10:13]
	v_mfma_f32_16x16x32_bf16 v[62:65], v[134:137], v[166:169], v[62:65]
	v_mfma_f32_16x16x32_bf16 v[58:61], v[142:145], v[166:169], v[58:61]
	v_mfma_f32_16x16x32_bf16 v[46:49], v[134:137], v[174:177], v[46:49]
	v_mfma_f32_16x16x32_bf16 v[42:45], v[142:145], v[174:177], v[42:45]
	v_mfma_f32_16x16x32_bf16 v[30:33], v[134:137], v[182:185], v[30:33]
	v_mfma_f32_16x16x32_bf16 v[26:29], v[142:145], v[182:185], v[26:29]
	v_mfma_f32_16x16x32_bf16 v[14:17], v[134:137], v[202:205], v[14:17]
	v_mfma_f32_16x16x32_bf16 v[10:13], v[142:145], v[202:205], v[10:13]
	s_setprio 0
	s_setprio 1
	v_mfma_f32_16x16x32_bf16 v[54:57], v[146:149], v[162:165], v[54:57]
	v_mfma_f32_16x16x32_bf16 v[50:53], v[154:157], v[162:165], v[50:53]
	v_mfma_f32_16x16x32_bf16 v[38:41], v[146:149], v[170:173], v[38:41]
	v_mfma_f32_16x16x32_bf16 v[34:37], v[154:157], v[170:173], v[34:37]
	v_mfma_f32_16x16x32_bf16 v[22:25], v[146:149], v[178:181], v[22:25]
	v_mfma_f32_16x16x32_bf16 v[18:21], v[154:157], v[178:181], v[18:21]
	v_mfma_f32_16x16x32_bf16 v[6:9], v[146:149], v[198:201], v[6:9]
	v_mfma_f32_16x16x32_bf16 v[2:5], v[154:157], v[198:201], v[2:5]
	v_mfma_f32_16x16x32_bf16 v[54:57], v[150:153], v[166:169], v[54:57]
	v_mfma_f32_16x16x32_bf16 v[50:53], v[158:161], v[166:169], v[50:53]
	v_mfma_f32_16x16x32_bf16 v[38:41], v[150:153], v[174:177], v[38:41]
	v_mfma_f32_16x16x32_bf16 v[34:37], v[158:161], v[174:177], v[34:37]
	v_mfma_f32_16x16x32_bf16 v[22:25], v[150:153], v[182:185], v[22:25]
	v_mfma_f32_16x16x32_bf16 v[18:21], v[158:161], v[182:185], v[18:21]
	v_mfma_f32_16x16x32_bf16 v[6:9], v[150:153], v[202:205], v[6:9]
	v_mfma_f32_16x16x32_bf16 v[2:5], v[158:161], v[202:205], v[2:5]
	s_setprio 0
	s_barrier
	s_add_i32 s1, 0, 0x18000
	s_add_i32 s47, 0, 0x1c000
	v_add_u32_e32 v142, s1, v234
	v_add_u32_e32 v158, s47, v234
	ds_read_b128 v[130:133], v142
	ds_read_b128 v[134:137], v142 offset:1024
	ds_read_b128 v[138:141], v142 offset:2048
	ds_read_b128 v[142:145], v142 offset:3072
	ds_read_b128 v[146:149], v158
	ds_read_b128 v[150:153], v158 offset:1024
	ds_read_b128 v[154:157], v158 offset:2048
	ds_read_b128 v[158:161], v158 offset:3072
	s_add_u32 s34, s34, s16
	s_addc_u32 s35, s35, 0
	s_mov_b32 m0, s61
	v_lshl_add_u64 v[218:219], s[34:35], 0, v[186:187]
	ds_read_b128 v[162:165], v238 offset:32768
	ds_read_b128 v[166:169], v238 offset:33792
	ds_read_b128 v[170:173], v238 offset:34816
	ds_read_b128 v[174:177], v238 offset:35840
	ds_read_b128 v[178:181], v238 offset:36864
	ds_read_b128 v[182:185], v238 offset:37888
	ds_read_b128 v[198:201], v238 offset:38912
	ds_read_b128 v[202:205], v238 offset:39936
	global_load_lds_dwordx4 v[218:219], off
	v_lshl_add_u64 v[218:219], s[34:35], 0, v[190:191]
	s_mov_b32 m0, s71
	s_nop 0
	global_load_lds_dwordx4 v[218:219], off
	s_waitcnt vmcnt(8)
	s_waitcnt lgkmcnt(0)
	s_barrier
	s_setprio 1
	s_waitcnt lgkmcnt(0)
	v_mfma_f32_16x16x32_bf16 v[126:129], v[130:133], v[162:165], v[126:129]
	v_mfma_f32_16x16x32_bf16 v[122:125], v[138:141], v[162:165], v[122:125]
	v_mfma_f32_16x16x32_bf16 v[118:121], v[130:133], v[170:173], v[118:121]
	v_mfma_f32_16x16x32_bf16 v[102:105], v[138:141], v[170:173], v[102:105]
	v_mfma_f32_16x16x32_bf16 v[94:97], v[130:133], v[178:181], v[94:97]
	v_mfma_f32_16x16x32_bf16 v[90:93], v[138:141], v[178:181], v[90:93]
	v_mfma_f32_16x16x32_bf16 v[78:81], v[130:133], v[198:201], v[78:81]
	v_mfma_f32_16x16x32_bf16 v[74:77], v[138:141], v[198:201], v[74:77]
	v_mfma_f32_16x16x32_bf16 v[126:129], v[134:137], v[166:169], v[126:129]
	v_mfma_f32_16x16x32_bf16 v[122:125], v[142:145], v[166:169], v[122:125]
	v_mfma_f32_16x16x32_bf16 v[118:121], v[134:137], v[174:177], v[118:121]
	v_mfma_f32_16x16x32_bf16 v[102:105], v[142:145], v[174:177], v[102:105]
	v_mfma_f32_16x16x32_bf16 v[94:97], v[134:137], v[182:185], v[94:97]
	v_mfma_f32_16x16x32_bf16 v[90:93], v[142:145], v[182:185], v[90:93]
	v_mfma_f32_16x16x32_bf16 v[78:81], v[134:137], v[202:205], v[78:81]
	v_mfma_f32_16x16x32_bf16 v[74:77], v[142:145], v[202:205], v[74:77]
	s_setprio 0
	s_setprio 1
	v_mfma_f32_16x16x32_bf16 v[114:117], v[146:149], v[162:165], v[114:117]
	v_mfma_f32_16x16x32_bf16 v[110:113], v[154:157], v[162:165], v[110:113]
	v_mfma_f32_16x16x32_bf16 v[106:109], v[146:149], v[170:173], v[106:109]
	v_mfma_f32_16x16x32_bf16 v[98:101], v[154:157], v[170:173], v[98:101]
	v_mfma_f32_16x16x32_bf16 v[86:89], v[146:149], v[178:181], v[86:89]
	v_mfma_f32_16x16x32_bf16 v[82:85], v[154:157], v[178:181], v[82:85]
	v_mfma_f32_16x16x32_bf16 v[70:73], v[146:149], v[198:201], v[70:73]
	v_mfma_f32_16x16x32_bf16 v[66:69], v[154:157], v[198:201], v[66:69]
	v_mfma_f32_16x16x32_bf16 v[114:117], v[150:153], v[166:169], v[114:117]
	v_mfma_f32_16x16x32_bf16 v[110:113], v[158:161], v[166:169], v[110:113]
	v_mfma_f32_16x16x32_bf16 v[106:109], v[150:153], v[174:177], v[106:109]
	v_mfma_f32_16x16x32_bf16 v[98:101], v[158:161], v[174:177], v[98:101]
	v_mfma_f32_16x16x32_bf16 v[86:89], v[150:153], v[182:185], v[86:89]
	v_mfma_f32_16x16x32_bf16 v[82:85], v[158:161], v[182:185], v[82:85]
	v_mfma_f32_16x16x32_bf16 v[70:73], v[150:153], v[202:205], v[70:73]
	v_mfma_f32_16x16x32_bf16 v[66:69], v[158:161], v[202:205], v[66:69]
	s_setprio 0
	s_barrier
	s_add_i32 s1, s1, s57
	v_lshl_add_u64 v[206:207], v[206:207], 0, s[36:37]
	s_mov_b32 m0, s1
	ds_read_b128 v[162:165], v238 offset:49152
	ds_read_b128 v[166:169], v238 offset:50176
	ds_read_b128 v[170:173], v238 offset:51200
	ds_read_b128 v[174:177], v238 offset:52224
	ds_read_b128 v[178:181], v238 offset:53248
	ds_read_b128 v[182:185], v238 offset:54272
	ds_read_b128 v[198:201], v238 offset:55296
	ds_read_b128 v[202:205], v238 offset:56320
	global_load_lds_dwordx4 v[206:207], off
	v_lshl_add_u64 v[206:207], v[208:209], 0, s[36:37]
	s_add_i32 m0, s1, 0x2000
	s_add_i32 s1, s47, s57
	global_load_lds_dwordx4 v[206:207], off
	v_lshl_add_u64 v[206:207], v[210:211], 0, s[36:37]
	s_mov_b32 m0, s1
	s_nop 0
	global_load_lds_dwordx4 v[206:207], off
	v_lshl_add_u64 v[206:207], v[212:213], 0, s[36:37]
	s_add_i32 m0, s1, 0x2000
	s_nop 0
	global_load_lds_dwordx4 v[206:207], off
	v_lshl_add_u64 v[206:207], v[214:215], 0, s[100:101]
	s_mov_b32 m0, s64
	s_nop 0
	global_load_lds_dwordx4 v[206:207], off
	v_lshl_add_u64 v[206:207], v[216:217], 0, s[100:101]
	s_mov_b32 m0, s65
	s_nop 0
	global_load_lds_dwordx4 v[206:207], off
	s_waitcnt vmcnt(8)
	s_waitcnt lgkmcnt(0)
	s_barrier
	s_setprio 1
	s_waitcnt lgkmcnt(0)
	v_mfma_f32_16x16x32_bf16 v[62:65], v[130:133], v[162:165], v[62:65]
	v_mfma_f32_16x16x32_bf16 v[58:61], v[138:141], v[162:165], v[58:61]
	v_mfma_f32_16x16x32_bf16 v[46:49], v[130:133], v[170:173], v[46:49]
	v_mfma_f32_16x16x32_bf16 v[42:45], v[138:141], v[170:173], v[42:45]
	v_mfma_f32_16x16x32_bf16 v[30:33], v[130:133], v[178:181], v[30:33]
	v_mfma_f32_16x16x32_bf16 v[26:29], v[138:141], v[178:181], v[26:29]
	v_mfma_f32_16x16x32_bf16 v[14:17], v[130:133], v[198:201], v[14:17]
	v_mfma_f32_16x16x32_bf16 v[10:13], v[138:141], v[198:201], v[10:13]
	v_mfma_f32_16x16x32_bf16 v[62:65], v[134:137], v[166:169], v[62:65]
	v_mfma_f32_16x16x32_bf16 v[58:61], v[142:145], v[166:169], v[58:61]
	v_mfma_f32_16x16x32_bf16 v[46:49], v[134:137], v[174:177], v[46:49]
	v_mfma_f32_16x16x32_bf16 v[42:45], v[142:145], v[174:177], v[42:45]
	v_mfma_f32_16x16x32_bf16 v[30:33], v[134:137], v[182:185], v[30:33]
	v_mfma_f32_16x16x32_bf16 v[26:29], v[142:145], v[182:185], v[26:29]
	v_mfma_f32_16x16x32_bf16 v[14:17], v[134:137], v[202:205], v[14:17]
	v_mfma_f32_16x16x32_bf16 v[10:13], v[142:145], v[202:205], v[10:13]
	s_setprio 0
	s_setprio 1
	v_mfma_f32_16x16x32_bf16 v[54:57], v[146:149], v[162:165], v[54:57]
	v_mfma_f32_16x16x32_bf16 v[50:53], v[154:157], v[162:165], v[50:53]
	v_mfma_f32_16x16x32_bf16 v[38:41], v[146:149], v[170:173], v[38:41]
	v_mfma_f32_16x16x32_bf16 v[34:37], v[154:157], v[170:173], v[34:37]
	v_mfma_f32_16x16x32_bf16 v[22:25], v[146:149], v[178:181], v[22:25]
	v_mfma_f32_16x16x32_bf16 v[18:21], v[154:157], v[178:181], v[18:21]
	v_mfma_f32_16x16x32_bf16 v[6:9], v[146:149], v[198:201], v[6:9]
	v_mfma_f32_16x16x32_bf16 v[2:5], v[154:157], v[198:201], v[2:5]
	v_mfma_f32_16x16x32_bf16 v[54:57], v[150:153], v[166:169], v[54:57]
	v_mfma_f32_16x16x32_bf16 v[50:53], v[158:161], v[166:169], v[50:53]
	v_mfma_f32_16x16x32_bf16 v[38:41], v[150:153], v[174:177], v[38:41]
	v_mfma_f32_16x16x32_bf16 v[34:37], v[158:161], v[174:177], v[34:37]
	v_mfma_f32_16x16x32_bf16 v[22:25], v[150:153], v[182:185], v[22:25]
	v_mfma_f32_16x16x32_bf16 v[18:21], v[158:161], v[182:185], v[18:21]
	v_mfma_f32_16x16x32_bf16 v[6:9], v[150:153], v[202:205], v[6:9]
	v_mfma_f32_16x16x32_bf16 v[2:5], v[158:161], v[202:205], v[2:5]
	s_setprio 0
	s_barrier
	s_lshl_b32 s1, s100, 1
	s_add_u32 s80, s80, s1
	s_addc_u32 s81, s81, 0
	s_add_u32 vcc_lo, vcc_lo, 0x100
	s_addc_u32 vcc_hi, vcc_hi, 0
	s_cmp_ge_u32 s0, s91
	s_mov_b32 s34, s0
	s_cbranch_scc0 .LBB0_169
	v_readlane_b32 s0, v243, 28
	v_readlane_b32 s1, v243, 29
	s_and_b64 vcc, exec, s[0:1]
	s_cbranch_vccz .LBB0_174
	s_barrier
	v_lshl_add_u32 v198, s99, 8, v1
	s_cmp_lt_i32 s70, 1
	s_mov_b64 s[34:35], -1
	s_cbranch_scc0 .LBB0_175

.LBB0_173:
	v_ashrrev_i32_e32 v199, 31, v198
	v_lshl_add_u64 v[132:133], v[198:199], 2, s[50:51]
	global_load_dword v136, v[132:133], off
	global_load_dword v137, v[132:133], off offset:64
	v_and_b32_e32 v130, 63, v237
	v_and_b32_e32 v134, 64, v237
	v_lshl_or_b32 v130, v134, 8, v130
	s_mul_i32 s0, s99, 0xb0000
	s_lshl_b32 s1, s88, 15
	s_add_i32 s0, s0, s1
	s_waitcnt lgkmcnt(0)
	v_add_u32_e32 v130, s0, v130
	v_lshl_add_u32 v134, v1, 6, v130
	global_load_dword v135, v[132:133], off offset:128
	global_load_dword v138, v[132:133], off offset:192
	global_load_dword v139, v[132:133], off offset:512
	global_load_dword v140, v[132:133], off offset:576
	global_load_dword v131, v[132:133], off offset:640
	global_load_dword v130, v[132:133], off offset:704
	v_lshlrev_b32_e32 v133, 1, v134
	s_movk_i32 s0, 0x1400
	s_waitcnt vmcnt(0)
	v_fmamk_f32 v132, v136, 0x3a800000, v221
	v_rsq_f32_e32 v132, v132
	v_fmamk_f32 v136, v137, 0x3a800000, v221
	v_rsq_f32_e32 v136, v136
	v_pk_mul_f32 v[126:127], v[126:127], v[132:133] op_sel_hi:[1,0]
	v_pk_mul_f32 v[114:115], v[114:115], v[132:133] op_sel_hi:[1,0]
	v_pk_mul_f32 v[128:129], v[128:129], v[132:133] op_sel_hi:[1,0]
	v_pk_mul_f32 v[116:117], v[116:117], v[132:133] op_sel_hi:[1,0]
	v_pk_mul_f32 v[122:123], v[122:123], v[132:133] op_sel_hi:[1,0]
	v_pk_mul_f32 v[110:111], v[110:111], v[132:133] op_sel_hi:[1,0]
	v_pk_mul_f32 v[124:125], v[124:125], v[132:133] op_sel_hi:[1,0]
	v_pk_mul_f32 v[112:113], v[112:113], v[132:133] op_sel_hi:[1,0]
	v_pk_mul_f32 v[118:119], v[118:119], v[136:137] op_sel_hi:[1,0]
	v_pk_mul_f32 v[106:107], v[106:107], v[136:137] op_sel_hi:[1,0]
	v_pk_mul_f32 v[120:121], v[120:121], v[136:137] op_sel_hi:[1,0]
	v_pk_mul_f32 v[108:109], v[108:109], v[136:137] op_sel_hi:[1,0]
	v_pk_mul_f32 v[102:103], v[102:103], v[136:137] op_sel_hi:[1,0]
	v_mul_f32_e32 v132, 0xbfb8aa3b, v126
	v_pk_mul_f32 v[114:115], v[126:127], v[114:115]
	v_mul_f32_e32 v126, 0xbfb8aa3b, v127
	v_mul_f32_e32 v127, 0xbfb8aa3b, v128
	v_pk_mul_f32 v[116:117], v[128:129], v[116:117]
	v_mul_f32_e32 v128, 0xbfb8aa3b, v129
	v_mul_f32_e32 v129, 0xbfb8aa3b, v122
	v_pk_mul_f32 v[110:111], v[122:123], v[110:111]
	v_mul_f32_e32 v122, 0xbfb8aa3b, v123
	v_mul_f32_e32 v123, 0xbfb8aa3b, v124
	v_pk_mul_f32 v[112:113], v[124:125], v[112:113]
	v_mul_f32_e32 v124, 0xbfb8aa3b, v125
	v_mul_f32_e32 v125, 0xbfb8aa3b, v118
	v_pk_mul_f32 v[106:107], v[118:119], v[106:107]
	v_mul_f32_e32 v118, 0xbfb8aa3b, v119
	v_mul_f32_e32 v119, 0xbfb8aa3b, v120
	v_pk_mul_f32 v[108:109], v[120:121], v[108:109]
	v_mul_f32_e32 v120, 0xbfb8aa3b, v121
	v_mul_f32_e32 v121, 0xbfb8aa3b, v102
	v_exp_f32_e32 v132, v132
	v_exp_f32_e32 v126, v126
	v_exp_f32_e32 v127, v127
	v_exp_f32_e32 v128, v128
	v_exp_f32_e32 v129, v129
	v_exp_f32_e32 v122, v122
	v_exp_f32_e32 v123, v123
	v_exp_f32_e32 v124, v124
	v_mul_f32_e32 v137, 0xbfb8aa3b, v103
	v_exp_f32_e32 v125, v125
	v_exp_f32_e32 v118, v118
	v_exp_f32_e32 v119, v119
	v_exp_f32_e32 v120, v120
	v_exp_f32_e32 v121, v121
	v_exp_f32_e32 v137, v137
	v_add_f32_e32 v132, 1.0, v132
	v_add_f32_e32 v126, 1.0, v126
	v_add_f32_e32 v127, 1.0, v127
	v_add_f32_e32 v128, 1.0, v128
	v_add_f32_e32 v129, 1.0, v129
	v_add_f32_e32 v141, 1.0, v122
	v_add_f32_e32 v142, 1.0, v123
	v_add_f32_e32 v143, 1.0, v124
	v_add_f32_e32 v144, 1.0, v125
	v_add_f32_e32 v145, 1.0, v118
	v_add_f32_e32 v146, 1.0, v119
	v_add_f32_e32 v147, 1.0, v120
	v_add_f32_e32 v148, 1.0, v121
	v_rcp_f32_e32 v118, v132
	v_rcp_f32_e32 v119, v126
	v_rcp_f32_e32 v120, v127
	v_rcp_f32_e32 v121, v128
	v_rcp_f32_e32 v122, v129
	v_rcp_f32_e32 v123, v141
	v_rcp_f32_e32 v124, v142
	v_rcp_f32_e32 v125, v143
	v_rcp_f32_e32 v126, v144
	v_rcp_f32_e32 v127, v145
	v_rcp_f32_e32 v128, v146
	v_rcp_f32_e32 v129, v147
	v_pk_mul_f32 v[98:99], v[98:99], v[136:137] op_sel_hi:[1,0]
	v_pk_mul_f32 v[114:115], v[114:115], v[118:119]
	v_pk_mul_f32 v[98:99], v[102:103], v[98:99]
	v_pk_mul_f32 v[102:103], v[104:105], v[136:137] op_sel_hi:[1,0]
	v_pk_mul_f32 v[116:117], v[116:117], v[120:121]
	v_mul_f32_e32 v104, 0xbfb8aa3b, v102
	v_mul_f32_e32 v105, 0xbfb8aa3b, v103
	v_pk_mul_f32 v[110:111], v[110:111], v[122:123]
	v_pk_mul_f32 v[112:113], v[112:113], v[124:125]
	v_exp_f32_e32 v104, v104
	v_exp_f32_e32 v105, v105
	v_pk_mul_f32 v[118:119], v[106:107], v[126:127]
	v_pk_mul_f32 v[120:121], v[108:109], v[128:129]
	v_cvt_pk_bf16_f32 v106, v114, v115
	v_cvt_pk_bf16_f32 v107, v116, v117
	v_cvt_pk_bf16_f32 v108, v110, v111
	v_cvt_pk_bf16_f32 v109, v112, v113
	buffer_store_dwordx4 v[106:109], v133, s[20:23], 0 offen sc1
	v_add_f32_e32 v104, 1.0, v104
	v_add_f32_e32 v105, 1.0, v105
	v_add_f32_e32 v107, 1.0, v137
	v_rcp_f32_e32 v106, v148
	v_rcp_f32_e32 v107, v107
	v_rcp_f32_e32 v104, v104
	v_rcp_f32_e32 v105, v105
	v_pk_mul_f32 v[106:107], v[98:99], v[106:107]
	v_pk_mul_f32 v[98:99], v[100:101], v[136:137] op_sel_hi:[1,0]
	s_nop 0
	v_pk_mul_f32 v[98:99], v[102:103], v[98:99]
	s_nop 0
	v_pk_mul_f32 v[102:103], v[98:99], v[104:105]
	v_fmamk_f32 v98, v135, 0x3a800000, v221
	v_rsq_f32_e32 v104, v98
	v_add_u32_e32 v105, 0x400, v134
	v_lshlrev_b32_e32 v108, 1, v105
	v_cvt_pk_bf16_f32 v98, v118, v119
	v_pk_mul_f32 v[94:95], v[94:95], v[104:105] op_sel_hi:[1,0]
	v_cvt_pk_bf16_f32 v99, v120, v121
	v_mul_f32_e32 v100, 0xbfb8aa3b, v94
	v_exp_f32_e32 v109, v100
	v_cvt_pk_bf16_f32 v100, v106, v107
	v_cvt_pk_bf16_f32 v101, v102, v103
	buffer_store_dwordx4 v[98:101], v108, s[20:23], 0 offen sc1
	v_pk_mul_f32 v[86:87], v[86:87], v[104:105] op_sel_hi:[1,0]
	v_pk_mul_f32 v[90:91], v[90:91], v[104:105] op_sel_hi:[1,0]
	v_mul_f32_e32 v99, 0xbfb8aa3b, v95
	v_exp_f32_e32 v99, v99
	v_add_f32_e32 v98, 1.0, v109
	v_pk_mul_f32 v[86:87], v[94:95], v[86:87]
	v_rcp_f32_e32 v98, v98
	v_add_f32_e32 v94, 1.0, v99
	v_rcp_f32_e32 v99, v94
	v_pk_mul_f32 v[94:95], v[96:97], v[104:105] op_sel_hi:[1,0]
	v_pk_mul_f32 v[88:89], v[88:89], v[104:105] op_sel_hi:[1,0]
	v_mul_f32_e32 v97, 0xbfb8aa3b, v95
	v_pk_mul_f32 v[86:87], v[86:87], v[98:99]
	v_mul_f32_e32 v98, 0xbfb8aa3b, v90
	v_pk_mul_f32 v[88:89], v[94:95], v[88:89]
	v_mul_f32_e32 v95, 0xbfb8aa3b, v91
	v_pk_mul_f32 v[82:83], v[82:83], v[104:105] op_sel_hi:[1,0]
	v_exp_f32_e32 v98, v98
	v_exp_f32_e32 v95, v95
	v_pk_mul_f32 v[82:83], v[90:91], v[82:83]
	v_pk_mul_f32 v[90:91], v[92:93], v[104:105] op_sel_hi:[1,0]
	v_mul_f32_e32 v96, 0xbfb8aa3b, v94
	v_mul_f32_e32 v92, 0xbfb8aa3b, v90
	v_mul_f32_e32 v93, 0xbfb8aa3b, v91
	v_exp_f32_e32 v92, v92
	v_exp_f32_e32 v93, v93
	v_add_f32_e32 v94, 1.0, v98
	v_add_f32_e32 v95, 1.0, v95
	v_rcp_f32_e32 v94, v94
	v_rcp_f32_e32 v95, v95
	v_add_f32_e32 v92, 1.0, v92
	v_add_f32_e32 v93, 1.0, v93
	v_rcp_f32_e32 v92, v92
	v_rcp_f32_e32 v93, v93
	v_exp_f32_e32 v96, v96
	v_exp_f32_e32 v97, v97
	v_pk_mul_f32 v[94:95], v[82:83], v[94:95]
	v_pk_mul_f32 v[82:83], v[84:85], v[104:105] op_sel_hi:[1,0]
	v_add_f32_e32 v96, 1.0, v96
	v_pk_mul_f32 v[82:83], v[90:91], v[82:83]
	v_add_f32_e32 v97, 1.0, v97
	v_pk_mul_f32 v[90:91], v[82:83], v[92:93]
	v_fmamk_f32 v82, v138, 0x3a800000, v221
	v_rsq_f32_e32 v92, v82
	v_rcp_f32_e32 v96, v96
	v_rcp_f32_e32 v97, v97
	v_add_u32_e32 v93, 0x400, v105
	v_pk_mul_f32 v[78:79], v[78:79], v[92:93] op_sel_hi:[1,0]
	v_cvt_pk_bf16_f32 v82, v86, v87
	v_pk_mul_f32 v[88:89], v[88:89], v[96:97]
	v_mul_f32_e32 v84, 0xbfb8aa3b, v78
	v_lshlrev_b32_e32 v96, 1, v93
	v_cvt_pk_bf16_f32 v83, v88, v89
	v_exp_f32_e32 v86, v84
	v_cvt_pk_bf16_f32 v84, v94, v95
	v_cvt_pk_bf16_f32 v85, v90, v91
	buffer_store_dwordx4 v[82:85], v96, s[20:23], 0 offen sc1
	v_pk_mul_f32 v[70:71], v[70:71], v[92:93] op_sel_hi:[1,0]
	v_pk_mul_f32 v[74:75], v[74:75], v[92:93] op_sel_hi:[1,0]
	v_mul_f32_e32 v83, 0xbfb8aa3b, v79
	v_exp_f32_e32 v83, v83
	v_add_f32_e32 v82, 1.0, v86
	v_pk_mul_f32 v[70:71], v[78:79], v[70:71]
	v_rcp_f32_e32 v82, v82
	v_add_f32_e32 v78, 1.0, v83
	v_rcp_f32_e32 v83, v78
	v_pk_mul_f32 v[78:79], v[80:81], v[92:93] op_sel_hi:[1,0]
	v_pk_mul_f32 v[72:73], v[72:73], v[92:93] op_sel_hi:[1,0]
	v_mul_f32_e32 v81, 0xbfb8aa3b, v79
	v_pk_mul_f32 v[70:71], v[70:71], v[82:83]
	v_mul_f32_e32 v82, 0xbfb8aa3b, v74
	v_pk_mul_f32 v[72:73], v[78:79], v[72:73]
	v_mul_f32_e32 v79, 0xbfb8aa3b, v75
	v_pk_mul_f32 v[66:67], v[66:67], v[92:93] op_sel_hi:[1,0]
	v_exp_f32_e32 v82, v82
	v_exp_f32_e32 v79, v79
	v_pk_mul_f32 v[66:67], v[74:75], v[66:67]
	v_pk_mul_f32 v[74:75], v[76:77], v[92:93] op_sel_hi:[1,0]
	v_mul_f32_e32 v80, 0xbfb8aa3b, v78
	v_mul_f32_e32 v76, 0xbfb8aa3b, v74
	v_mul_f32_e32 v77, 0xbfb8aa3b, v75
	v_exp_f32_e32 v76, v76
	v_exp_f32_e32 v77, v77
	v_add_f32_e32 v78, 1.0, v82
	v_add_f32_e32 v79, 1.0, v79
	v_rcp_f32_e32 v78, v78
	v_rcp_f32_e32 v79, v79
	v_add_f32_e32 v76, 1.0, v76
	v_add_f32_e32 v77, 1.0, v77
	v_rcp_f32_e32 v76, v76
	v_rcp_f32_e32 v77, v77
	v_exp_f32_e32 v80, v80
	v_exp_f32_e32 v81, v81
	v_pk_mul_f32 v[78:79], v[66:67], v[78:79]
	v_pk_mul_f32 v[66:67], v[68:69], v[92:93] op_sel_hi:[1,0]
	v_add_f32_e32 v80, 1.0, v80
	v_pk_mul_f32 v[66:67], v[74:75], v[66:67]
	v_add_f32_e32 v81, 1.0, v81
	v_pk_mul_f32 v[74:75], v[66:67], v[76:77]
	v_fmamk_f32 v66, v139, 0x3a800000, v221
	v_rsq_f32_e32 v76, v66
	v_rcp_f32_e32 v80, v80
	v_rcp_f32_e32 v81, v81
	v_add_u32_e32 v77, 0x400, v93
	v_pk_mul_f32 v[62:63], v[62:63], v[76:77] op_sel_hi:[1,0]
	v_cvt_pk_bf16_f32 v66, v70, v71
	v_pk_mul_f32 v[72:73], v[72:73], v[80:81]
	v_mul_f32_e32 v68, 0xbfb8aa3b, v62
	v_lshlrev_b32_e32 v80, 1, v77
	v_cvt_pk_bf16_f32 v67, v72, v73
	v_exp_f32_e32 v70, v68
	v_cvt_pk_bf16_f32 v68, v78, v79
	v_cvt_pk_bf16_f32 v69, v74, v75
	buffer_store_dwordx4 v[66:69], v80, s[20:23], 0 offen sc1
	v_pk_mul_f32 v[54:55], v[54:55], v[76:77] op_sel_hi:[1,0]
	v_pk_mul_f32 v[58:59], v[58:59], v[76:77] op_sel_hi:[1,0]
	v_mul_f32_e32 v67, 0xbfb8aa3b, v63
	v_exp_f32_e32 v67, v67
	v_add_f32_e32 v66, 1.0, v70
	v_pk_mul_f32 v[54:55], v[62:63], v[54:55]
	v_rcp_f32_e32 v66, v66
	v_add_f32_e32 v62, 1.0, v67
	v_rcp_f32_e32 v67, v62
	v_pk_mul_f32 v[62:63], v[64:65], v[76:77] op_sel_hi:[1,0]
	v_pk_mul_f32 v[56:57], v[56:57], v[76:77] op_sel_hi:[1,0]
	v_mul_f32_e32 v65, 0xbfb8aa3b, v63
	v_pk_mul_f32 v[54:55], v[54:55], v[66:67]
	v_mul_f32_e32 v66, 0xbfb8aa3b, v58
	v_pk_mul_f32 v[56:57], v[62:63], v[56:57]
	v_mul_f32_e32 v63, 0xbfb8aa3b, v59
	v_pk_mul_f32 v[50:51], v[50:51], v[76:77] op_sel_hi:[1,0]
	v_exp_f32_e32 v66, v66
	v_exp_f32_e32 v63, v63
	v_pk_mul_f32 v[50:51], v[58:59], v[50:51]
	v_pk_mul_f32 v[58:59], v[60:61], v[76:77] op_sel_hi:[1,0]
	v_mul_f32_e32 v64, 0xbfb8aa3b, v62
	v_mul_f32_e32 v60, 0xbfb8aa3b, v58
	v_mul_f32_e32 v61, 0xbfb8aa3b, v59
	v_exp_f32_e32 v60, v60
	v_exp_f32_e32 v61, v61
	v_add_f32_e32 v62, 1.0, v66
	v_add_f32_e32 v63, 1.0, v63
	v_rcp_f32_e32 v62, v62
	v_rcp_f32_e32 v63, v63
	v_add_f32_e32 v60, 1.0, v60
	v_add_f32_e32 v61, 1.0, v61
	v_rcp_f32_e32 v60, v60
	v_rcp_f32_e32 v61, v61
	v_exp_f32_e32 v64, v64
	v_exp_f32_e32 v65, v65
	v_pk_mul_f32 v[62:63], v[50:51], v[62:63]
	v_pk_mul_f32 v[50:51], v[52:53], v[76:77] op_sel_hi:[1,0]
	v_add_f32_e32 v64, 1.0, v64
	v_pk_mul_f32 v[50:51], v[58:59], v[50:51]
	v_add_f32_e32 v65, 1.0, v65
	v_pk_mul_f32 v[58:59], v[50:51], v[60:61]
	v_fmamk_f32 v50, v140, 0x3a800000, v221
	v_rsq_f32_e32 v60, v50
	v_rcp_f32_e32 v64, v64
	v_rcp_f32_e32 v65, v65
	v_add_u32_e32 v61, s0, v77
	v_pk_mul_f32 v[46:47], v[46:47], v[60:61] op_sel_hi:[1,0]
	v_cvt_pk_bf16_f32 v50, v54, v55
	v_pk_mul_f32 v[56:57], v[56:57], v[64:65]
	v_mul_f32_e32 v52, 0xbfb8aa3b, v46
	v_lshlrev_b32_e32 v64, 1, v61
	v_cvt_pk_bf16_f32 v51, v56, v57
	v_exp_f32_e32 v54, v52
	v_cvt_pk_bf16_f32 v52, v62, v63
	v_cvt_pk_bf16_f32 v53, v58, v59
	buffer_store_dwordx4 v[50:53], v64, s[20:23], 0 offen sc1
	v_pk_mul_f32 v[38:39], v[38:39], v[60:61] op_sel_hi:[1,0]
	v_pk_mul_f32 v[42:43], v[42:43], v[60:61] op_sel_hi:[1,0]
	v_mul_f32_e32 v51, 0xbfb8aa3b, v47
	v_exp_f32_e32 v51, v51
	v_add_f32_e32 v50, 1.0, v54
	v_pk_mul_f32 v[38:39], v[46:47], v[38:39]
	v_rcp_f32_e32 v50, v50
	v_add_f32_e32 v46, 1.0, v51
	v_rcp_f32_e32 v51, v46
	v_pk_mul_f32 v[46:47], v[48:49], v[60:61] op_sel_hi:[1,0]
	v_pk_mul_f32 v[40:41], v[40:41], v[60:61] op_sel_hi:[1,0]
	v_mul_f32_e32 v49, 0xbfb8aa3b, v47
	v_pk_mul_f32 v[38:39], v[38:39], v[50:51]
	v_mul_f32_e32 v50, 0xbfb8aa3b, v42
	v_pk_mul_f32 v[40:41], v[46:47], v[40:41]
	v_mul_f32_e32 v47, 0xbfb8aa3b, v43
	v_pk_mul_f32 v[34:35], v[34:35], v[60:61] op_sel_hi:[1,0]
	v_exp_f32_e32 v50, v50
	v_exp_f32_e32 v47, v47
	v_pk_mul_f32 v[34:35], v[42:43], v[34:35]
	v_pk_mul_f32 v[42:43], v[44:45], v[60:61] op_sel_hi:[1,0]
	v_mul_f32_e32 v48, 0xbfb8aa3b, v46
	v_mul_f32_e32 v44, 0xbfb8aa3b, v42
	v_mul_f32_e32 v45, 0xbfb8aa3b, v43
	v_exp_f32_e32 v44, v44
	v_exp_f32_e32 v45, v45
	v_add_f32_e32 v46, 1.0, v50
	v_add_f32_e32 v47, 1.0, v47
	v_rcp_f32_e32 v46, v46
	v_rcp_f32_e32 v47, v47
	v_add_f32_e32 v44, 1.0, v44
	v_add_f32_e32 v45, 1.0, v45
	v_rcp_f32_e32 v44, v44
	v_rcp_f32_e32 v45, v45
	v_exp_f32_e32 v48, v48
	v_exp_f32_e32 v49, v49
	v_pk_mul_f32 v[46:47], v[34:35], v[46:47]
	v_pk_mul_f32 v[34:35], v[36:37], v[60:61] op_sel_hi:[1,0]
	v_add_f32_e32 v48, 1.0, v48
	v_pk_mul_f32 v[34:35], v[42:43], v[34:35]
	v_add_f32_e32 v49, 1.0, v49
	v_pk_mul_f32 v[42:43], v[34:35], v[44:45]
	v_fmamk_f32 v34, v131, 0x3a800000, v221
	v_rsq_f32_e32 v44, v34
	v_rcp_f32_e32 v48, v48
	v_rcp_f32_e32 v49, v49
	v_add_u32_e32 v45, 0x400, v61
	v_pk_mul_f32 v[30:31], v[30:31], v[44:45] op_sel_hi:[1,0]
	v_cvt_pk_bf16_f32 v34, v38, v39
	v_pk_mul_f32 v[40:41], v[40:41], v[48:49]
	v_mul_f32_e32 v36, 0xbfb8aa3b, v30
	v_lshlrev_b32_e32 v48, 1, v45
	v_cvt_pk_bf16_f32 v35, v40, v41
	v_exp_f32_e32 v38, v36
	v_cvt_pk_bf16_f32 v36, v46, v47
	v_cvt_pk_bf16_f32 v37, v42, v43
	buffer_store_dwordx4 v[34:37], v48, s[20:23], 0 offen sc1
	v_pk_mul_f32 v[22:23], v[22:23], v[44:45] op_sel_hi:[1,0]
	v_pk_mul_f32 v[26:27], v[26:27], v[44:45] op_sel_hi:[1,0]
	v_mul_f32_e32 v35, 0xbfb8aa3b, v31
	v_exp_f32_e32 v35, v35
	v_add_f32_e32 v34, 1.0, v38
	v_pk_mul_f32 v[22:23], v[30:31], v[22:23]
	v_rcp_f32_e32 v34, v34
	v_add_f32_e32 v30, 1.0, v35
	v_rcp_f32_e32 v35, v30
	v_pk_mul_f32 v[30:31], v[32:33], v[44:45] op_sel_hi:[1,0]
	v_pk_mul_f32 v[24:25], v[24:25], v[44:45] op_sel_hi:[1,0]
	v_mul_f32_e32 v33, 0xbfb8aa3b, v31
	v_pk_mul_f32 v[22:23], v[22:23], v[34:35]
	v_mul_f32_e32 v34, 0xbfb8aa3b, v26
	v_pk_mul_f32 v[24:25], v[30:31], v[24:25]
	v_mul_f32_e32 v31, 0xbfb8aa3b, v27
	v_pk_mul_f32 v[18:19], v[18:19], v[44:45] op_sel_hi:[1,0]
	v_exp_f32_e32 v34, v34
	v_exp_f32_e32 v31, v31
	v_pk_mul_f32 v[18:19], v[26:27], v[18:19]
	v_pk_mul_f32 v[26:27], v[28:29], v[44:45] op_sel_hi:[1,0]
	v_mul_f32_e32 v32, 0xbfb8aa3b, v30
	v_mul_f32_e32 v28, 0xbfb8aa3b, v26
	v_mul_f32_e32 v29, 0xbfb8aa3b, v27
	v_exp_f32_e32 v28, v28
	v_exp_f32_e32 v29, v29
	v_add_f32_e32 v30, 1.0, v34
	v_add_f32_e32 v31, 1.0, v31
	v_rcp_f32_e32 v30, v30
	v_rcp_f32_e32 v31, v31
	v_add_f32_e32 v28, 1.0, v28
	v_add_f32_e32 v29, 1.0, v29
	v_rcp_f32_e32 v28, v28
	v_rcp_f32_e32 v29, v29
	v_exp_f32_e32 v32, v32
	v_exp_f32_e32 v33, v33
	v_pk_mul_f32 v[30:31], v[18:19], v[30:31]
	v_pk_mul_f32 v[18:19], v[20:21], v[44:45] op_sel_hi:[1,0]
	v_add_f32_e32 v32, 1.0, v32
	v_pk_mul_f32 v[18:19], v[26:27], v[18:19]
	v_add_f32_e32 v33, 1.0, v33
	v_pk_mul_f32 v[26:27], v[18:19], v[28:29]
	v_fmamk_f32 v18, v130, 0x3a800000, v221
	v_rsq_f32_e32 v28, v18
	v_rcp_f32_e32 v32, v32
	v_rcp_f32_e32 v33, v33
	v_add_u32_e32 v29, 0x400, v45
	v_pk_mul_f32 v[14:15], v[14:15], v[28:29] op_sel_hi:[1,0]
	v_cvt_pk_bf16_f32 v18, v22, v23
	v_pk_mul_f32 v[24:25], v[24:25], v[32:33]
	v_mul_f32_e32 v20, 0xbfb8aa3b, v14
	v_lshlrev_b32_e32 v32, 1, v29
	v_cvt_pk_bf16_f32 v19, v24, v25
	v_exp_f32_e32 v22, v20
	v_cvt_pk_bf16_f32 v20, v30, v31
	v_cvt_pk_bf16_f32 v21, v26, v27
	buffer_store_dwordx4 v[18:21], v32, s[20:23], 0 offen sc1
	v_pk_mul_f32 v[6:7], v[6:7], v[28:29] op_sel_hi:[1,0]
	v_pk_mul_f32 v[10:11], v[10:11], v[28:29] op_sel_hi:[1,0]
	v_mul_f32_e32 v19, 0xbfb8aa3b, v15
	v_exp_f32_e32 v19, v19
	v_add_f32_e32 v18, 1.0, v22
	v_pk_mul_f32 v[6:7], v[14:15], v[6:7]
	v_rcp_f32_e32 v18, v18
	v_add_f32_e32 v14, 1.0, v19
	v_rcp_f32_e32 v19, v14
	v_pk_mul_f32 v[14:15], v[16:17], v[28:29] op_sel_hi:[1,0]
	v_pk_mul_f32 v[8:9], v[8:9], v[28:29] op_sel_hi:[1,0]
	v_mul_f32_e32 v17, 0xbfb8aa3b, v15
	v_pk_mul_f32 v[6:7], v[6:7], v[18:19]
	v_mul_f32_e32 v18, 0xbfb8aa3b, v10
	v_pk_mul_f32 v[8:9], v[14:15], v[8:9]
	v_mul_f32_e32 v15, 0xbfb8aa3b, v11
	v_pk_mul_f32 v[2:3], v[2:3], v[28:29] op_sel_hi:[1,0]
	v_exp_f32_e32 v18, v18
	v_exp_f32_e32 v15, v15
	v_pk_mul_f32 v[2:3], v[10:11], v[2:3]
	v_pk_mul_f32 v[10:11], v[12:13], v[28:29] op_sel_hi:[1,0]
	v_mul_f32_e32 v16, 0xbfb8aa3b, v14
	v_mul_f32_e32 v12, 0xbfb8aa3b, v10
	v_mul_f32_e32 v13, 0xbfb8aa3b, v11
	v_exp_f32_e32 v16, v16
	v_exp_f32_e32 v17, v17
	v_exp_f32_e32 v12, v12
	v_exp_f32_e32 v13, v13
	v_add_f32_e32 v14, 1.0, v18
	v_add_f32_e32 v15, 1.0, v15
	v_rcp_f32_e32 v14, v14
	v_rcp_f32_e32 v15, v15
	v_add_f32_e32 v16, 1.0, v16
	v_add_f32_e32 v17, 1.0, v17
	v_add_f32_e32 v12, 1.0, v12
	v_add_f32_e32 v13, 1.0, v13
	v_rcp_f32_e32 v16, v16
	v_rcp_f32_e32 v17, v17
	v_rcp_f32_e32 v12, v12
	v_rcp_f32_e32 v13, v13
	v_pk_mul_f32 v[14:15], v[2:3], v[14:15]
	v_pk_mul_f32 v[2:3], v[4:5], v[28:29] op_sel_hi:[1,0]
	v_pk_mul_f32 v[8:9], v[8:9], v[16:17]
	v_pk_mul_f32 v[2:3], v[10:11], v[2:3]
	v_cvt_pk_bf16_f32 v4, v14, v15
	v_pk_mul_f32 v[10:11], v[2:3], v[12:13]
	v_add_u32_e32 v12, 0x400, v29
	v_lshlrev_b32_e32 v12, 1, v12
	v_cvt_pk_bf16_f32 v2, v6, v7
	v_cvt_pk_bf16_f32 v3, v8, v9
	v_cvt_pk_bf16_f32 v5, v10, v11
	buffer_store_dwordx4 v[2:5], v12, s[20:23], 0 offen sc1
	s_and_b64 vcc, exec, s[40:41]
	s_mov_b64 s[34:35], -1
	s_cbranch_vccnz .LBB0_161
	s_branch .LBB0_225

	.amdhsa_kernel _Z14fwd_megakernel6Params
		.amdhsa_group_segment_fixed_size 0
		.amdhsa_private_segment_fixed_size 0
		.amdhsa_kernarg_size 472
		.amdhsa_user_sgpr_count 2
		.amdhsa_user_sgpr_dispatch_ptr 0
		.amdhsa_user_sgpr_queue_ptr 0
		.amdhsa_user_sgpr_kernarg_segment_ptr 1
		.amdhsa_user_sgpr_dispatch_id 0
		.amdhsa_user_sgpr_kernarg_preload_length 0
		.amdhsa_user_sgpr_kernarg_preload_offset 0
		.amdhsa_user_sgpr_private_segment_size 0
		.amdhsa_uses_dynamic_stack 0
		.amdhsa_enable_private_segment 0
		.amdhsa_system_sgpr_workgroup_id_x 1
		.amdhsa_system_sgpr_workgroup_id_y 0
		.amdhsa_system_sgpr_workgroup_id_z 0
		.amdhsa_system_sgpr_workgroup_info 0
		.amdhsa_system_vgpr_workitem_id 2
		.amdhsa_next_free_vgpr 251
		.amdhsa_next_free_sgpr 102
		.amdhsa_accum_offset 252
		.amdhsa_reserve_vcc 1
		.amdhsa_float_round_mode_32 0
		.amdhsa_float_round_mode_16_64 0
		.amdhsa_float_denorm_mode_32 3
		.amdhsa_float_denorm_mode_16_64 3
		.amdhsa_dx10_clamp 1
		.amdhsa_ieee_mode 1
		.amdhsa_fp16_overflow 0
		.amdhsa_tg_split 0
		.amdhsa_exception_fp_ieee_invalid_op 0
		.amdhsa_exception_fp_denorm_src 0
		.amdhsa_exception_fp_ieee_div_zero 0
		.amdhsa_exception_fp_ieee_overflow 0
		.amdhsa_exception_fp_ieee_underflow 0
		.amdhsa_exception_fp_ieee_inexact 0
		.amdhsa_exception_int_div_zero 0
	.end_amdhsa_kernel

amdhsa.kernels:
  - .agpr_count:     0
    .args:
      - .offset:         0
        .size:           216
        .value_kind:     by_value
      - .offset:         216
        .size:           4
        .value_kind:     hidden_block_count_x
      - .offset:         220
        .size:           4
        .value_kind:     hidden_block_count_y
      - .offset:         224
        .size:           4
        .value_kind:     hidden_block_count_z
      - .offset:         228
        .size:           2
        .value_kind:     hidden_group_size_x
      - .offset:         230
        .size:           2
        .value_kind:     hidden_group_size_y
      - .offset:         232
        .size:           2
        .value_kind:     hidden_group_size_z
      - .offset:         234
        .size:           2
        .value_kind:     hidden_remainder_x
      - .offset:         236
        .size:           2
        .value_kind:     hidden_remainder_y
      - .offset:         238
        .size:           2
        .value_kind:     hidden_remainder_z
      - .offset:         256
        .size:           8
        .value_kind:     hidden_global_offset_x
      - .offset:         264
        .size:           8
        .value_kind:     hidden_global_offset_y
      - .offset:         272
        .size:           8
        .value_kind:     hidden_global_offset_z
      - .offset:         280
        .size:           2
        .value_kind:     hidden_grid_dims
      - .offset:         304
        .size:           8
        .value_kind:     hidden_multigrid_sync_arg
      - .offset:         336
        .size:           4
        .value_kind:     hidden_dynamic_lds_size
    .group_segment_fixed_size: 0
    .kernarg_segment_align: 8
    .kernarg_segment_size: 472
    .language:       OpenCL C
    .language_version:
      - 2
      - 0
    .max_flat_workgroup_size: 512
    .name:           _Z14fwd_megakernel6Params
    .private_segment_fixed_size: 0
    .sgpr_count: 108
    .sgpr_spill_count: 289
    .symbol:         _Z14fwd_megakernel6Params.kd
    .uniform_work_group_size: 1
    .uses_dynamic_stack: false
    .vgpr_count:     251
    .vgpr_spill_count: 0
    .wavefront_size: 64
